# carry step as four fmas; GELU scale constants folded (exact)
# speedup vs baseline: 1.0071x; 1.0026x over previous
.Lcarry_ld_done:
	s_waitcnt vmcnt(0)
	v_fma_f32 v52, -v42, v93, v136
	v_fma_f32 v53, v42, v92, v137
	v_fma_f32 v92, v41, v92, v52
	v_fma_f32 v93, v41, v93, v53
	s_cmp_le_u32 s41, 1
	s_cbranch_scc1 .Lcarry_done
	v_fma_f32 v52, -v42, v93, v138
	v_fma_f32 v53, v42, v92, v139
	v_fma_f32 v92, v41, v92, v52
	v_fma_f32 v93, v41, v93, v53
	s_cmp_le_u32 s41, 2
	s_cbranch_scc1 .Lcarry_done
	v_fma_f32 v52, -v42, v93, v140
	v_fma_f32 v53, v42, v92, v141
	v_fma_f32 v92, v41, v92, v52
	v_fma_f32 v93, v41, v93, v53
	s_cmp_le_u32 s41, 3
	s_cbranch_scc1 .Lcarry_done
	v_fma_f32 v52, -v42, v93, v142
	v_fma_f32 v53, v42, v92, v143
	v_fma_f32 v92, v41, v92, v52
	v_fma_f32 v93, v41, v93, v53
	s_cmp_le_u32 s41, 4
	s_cbranch_scc1 .Lcarry_done
	v_fma_f32 v52, -v42, v93, v144
	v_fma_f32 v53, v42, v92, v145
	v_fma_f32 v92, v41, v92, v52
	v_fma_f32 v93, v41, v93, v53
	s_cmp_le_u32 s41, 5
	s_cbranch_scc1 .Lcarry_done
	v_fma_f32 v52, -v42, v93, v146
	v_fma_f32 v53, v42, v92, v147
	v_fma_f32 v92, v41, v92, v52
	v_fma_f32 v93, v41, v93, v53
	s_cmp_le_u32 s41, 6
	s_cbranch_scc1 .Lcarry_done
	v_fma_f32 v52, -v42, v93, v148
	v_fma_f32 v53, v42, v92, v149
	v_fma_f32 v92, v41, v92, v52
	v_fma_f32 v93, v41, v93, v53
	s_cmp_le_u32 s41, 7
	s_cbranch_scc1 .Lcarry_done
	v_fma_f32 v52, -v42, v93, v150
	v_fma_f32 v53, v42, v92, v151
	v_fma_f32 v92, v41, v92, v52
	v_fma_f32 v93, v41, v93, v53
	s_cmp_le_u32 s41, 8
	s_cbranch_scc1 .Lcarry_done
	v_fma_f32 v52, -v42, v93, v152
	v_fma_f32 v53, v42, v92, v153
	v_fma_f32 v92, v41, v92, v52
	v_fma_f32 v93, v41, v93, v53
	s_cmp_le_u32 s41, 9
	s_cbranch_scc1 .Lcarry_done
	v_fma_f32 v52, -v42, v93, v154
	v_fma_f32 v53, v42, v92, v155
	v_fma_f32 v92, v41, v92, v52
	v_fma_f32 v93, v41, v93, v53
	s_cmp_le_u32 s41, 10
	s_cbranch_scc1 .Lcarry_done
	v_fma_f32 v52, -v42, v93, v156
	v_fma_f32 v53, v42, v92, v157
	v_fma_f32 v92, v41, v92, v52
	v_fma_f32 v93, v41, v93, v53
	s_cmp_le_u32 s41, 11
	s_cbranch_scc1 .Lcarry_done
	v_fma_f32 v52, -v42, v93, v158
	v_fma_f32 v53, v42, v92, v159
	v_fma_f32 v92, v41, v92, v52
	v_fma_f32 v93, v41, v93, v53
	s_cmp_le_u32 s41, 12
	s_cbranch_scc1 .Lcarry_done
	v_fma_f32 v52, -v42, v93, v160
	v_fma_f32 v53, v42, v92, v161
	v_fma_f32 v92, v41, v92, v52
	v_fma_f32 v93, v41, v93, v53
	s_cmp_le_u32 s41, 13
	s_cbranch_scc1 .Lcarry_done
	v_fma_f32 v52, -v42, v93, v162
	v_fma_f32 v53, v42, v92, v163
	v_fma_f32 v92, v41, v92, v52
	v_fma_f32 v93, v41, v93, v53
	s_cmp_le_u32 s41, 14
	s_cbranch_scc1 .Lcarry_done
	v_fma_f32 v52, -v42, v93, v164
	v_fma_f32 v53, v42, v92, v165
	v_fma_f32 v92, v41, v92, v52
	v_fma_f32 v93, v41, v93, v53
	s_cmp_le_u32 s41, 15
	s_cbranch_scc1 .Lcarry_done
	v_fma_f32 v52, -v42, v93, v166
	v_fma_f32 v53, v42, v92, v167
	v_fma_f32 v92, v41, v92, v52
	v_fma_f32 v93, v41, v93, v53
	s_cmp_le_u32 s41, 16
	s_cbranch_scc1 .Lcarry_done
	v_fma_f32 v52, -v42, v93, v168
	v_fma_f32 v53, v42, v92, v169
	v_fma_f32 v92, v41, v92, v52
	v_fma_f32 v93, v41, v93, v53
	s_cmp_le_u32 s41, 17
	s_cbranch_scc1 .Lcarry_done
	v_fma_f32 v52, -v42, v93, v170
	v_fma_f32 v53, v42, v92, v171
	v_fma_f32 v92, v41, v92, v52
	v_fma_f32 v93, v41, v93, v53
	s_cmp_le_u32 s41, 18
	s_cbranch_scc1 .Lcarry_done
	v_fma_f32 v52, -v42, v93, v172
	v_fma_f32 v53, v42, v92, v173
	v_fma_f32 v92, v41, v92, v52
	v_fma_f32 v93, v41, v93, v53
	s_cmp_le_u32 s41, 19
	s_cbranch_scc1 .Lcarry_done
	v_fma_f32 v52, -v42, v93, v174
	v_fma_f32 v53, v42, v92, v175
	v_fma_f32 v92, v41, v92, v52
	v_fma_f32 v93, v41, v93, v53
	s_cmp_le_u32 s41, 20
	s_cbranch_scc1 .Lcarry_done
	v_fma_f32 v52, -v42, v93, v176
	v_fma_f32 v53, v42, v92, v177
	v_fma_f32 v92, v41, v92, v52
	v_fma_f32 v93, v41, v93, v53
	s_cmp_le_u32 s41, 21
	s_cbranch_scc1 .Lcarry_done
	v_fma_f32 v52, -v42, v93, v178
	v_fma_f32 v53, v42, v92, v179
	v_fma_f32 v92, v41, v92, v52
	v_fma_f32 v93, v41, v93, v53
	s_cmp_le_u32 s41, 22
	s_cbranch_scc1 .Lcarry_done
	v_fma_f32 v52, -v42, v93, v180
	v_fma_f32 v53, v42, v92, v181
	v_fma_f32 v92, v41, v92, v52
	v_fma_f32 v93, v41, v93, v53
	s_cmp_le_u32 s41, 23
	s_cbranch_scc1 .Lcarry_done
	v_fma_f32 v52, -v42, v93, v182
	v_fma_f32 v53, v42, v92, v183
	v_fma_f32 v92, v41, v92, v52
	v_fma_f32 v93, v41, v93, v53
	s_cmp_le_u32 s41, 24
	s_cbranch_scc1 .Lcarry_done
	v_fma_f32 v52, -v42, v93, v184
	v_fma_f32 v53, v42, v92, v185
	v_fma_f32 v92, v41, v92, v52
	v_fma_f32 v93, v41, v93, v53
	s_cmp_le_u32 s41, 25
	s_cbranch_scc1 .Lcarry_done
	v_fma_f32 v52, -v42, v93, v186
	v_fma_f32 v53, v42, v92, v187
	v_fma_f32 v92, v41, v92, v52
	v_fma_f32 v93, v41, v93, v53
	s_cmp_le_u32 s41, 26
	s_cbranch_scc1 .Lcarry_done
	v_fma_f32 v52, -v42, v93, v188
	v_fma_f32 v53, v42, v92, v189
	v_fma_f32 v92, v41, v92, v52
	v_fma_f32 v93, v41, v93, v53
	s_cmp_le_u32 s41, 27
	s_cbranch_scc1 .Lcarry_done
	v_fma_f32 v52, -v42, v93, v190
	v_fma_f32 v53, v42, v92, v191
	v_fma_f32 v92, v41, v92, v52
	v_fma_f32 v93, v41, v93, v53
	s_cmp_le_u32 s41, 28
	s_cbranch_scc1 .Lcarry_done
	v_fma_f32 v52, -v42, v93, v202
	v_fma_f32 v53, v42, v92, v203
	v_fma_f32 v92, v41, v92, v52
	v_fma_f32 v93, v41, v93, v53
	s_cmp_le_u32 s41, 29
	s_cbranch_scc1 .Lcarry_done
	v_fma_f32 v52, -v42, v93, v204
	v_fma_f32 v53, v42, v92, v205
	v_fma_f32 v92, v41, v92, v52
	v_fma_f32 v93, v41, v93, v53
	s_cmp_le_u32 s41, 30
	s_cbranch_scc1 .Lcarry_done
	v_fma_f32 v52, -v42, v93, v206
	v_fma_f32 v53, v42, v92, v207
	v_fma_f32 v92, v41, v92, v52
	v_fma_f32 v93, v41, v93, v53

.LBB0_439:
	ds_read2_b32 v[122:123], v83 offset1:68
	ds_read2_b32 v[124:125], v83 offset0:136 offset1:204
	v_add_u32_e32 v121, 0x400, v83
	ds_read2_b32 v[126:127], v121 offset0:16 offset1:84
	ds_read2_b32 v[128:129], v121 offset0:152 offset1:220
	s_add_i32 s2, s2, 8
	s_waitcnt lgkmcnt(3)
	v_lshlrev_b32_e32 v136, 16, v122
	v_and_b32_e32 v137, 0xffff0000, v122
	v_fma_f32 v134, -v91, v93, v136
	v_fma_f32 v135, v91, v92, v137
	v_fma_f32 v92, v90, v92, v134
	v_fma_f32 v93, v90, v93, v135
	v_lshlrev_b32_e32 v136, 16, v123
	v_and_b32_e32 v137, 0xffff0000, v123
	v_fma_f32 v134, -v91, v93, v136
	v_fma_f32 v135, v91, v92, v137
	v_cvt_pk_bf16_f32 v130, v92, v93
	v_fma_f32 v92, v90, v92, v134
	v_fma_f32 v93, v90, v93, v135
	v_cvt_pk_bf16_f32 v131, v92, v93
	ds_write2_b32 v83, v130, v131 offset1:68
	s_waitcnt lgkmcnt(3)
	v_lshlrev_b32_e32 v136, 16, v124
	v_and_b32_e32 v137, 0xffff0000, v124
	v_fma_f32 v134, -v91, v93, v136
	v_fma_f32 v135, v91, v92, v137
	v_fma_f32 v92, v90, v92, v134
	v_fma_f32 v93, v90, v93, v135
	v_lshlrev_b32_e32 v136, 16, v125
	v_and_b32_e32 v137, 0xffff0000, v125
	v_fma_f32 v134, -v91, v93, v136
	v_fma_f32 v135, v91, v92, v137
	v_cvt_pk_bf16_f32 v132, v92, v93
	v_fma_f32 v92, v90, v92, v134
	v_fma_f32 v93, v90, v93, v135
	v_cvt_pk_bf16_f32 v133, v92, v93
	ds_write2_b32 v83, v132, v133 offset0:136 offset1:204
	s_waitcnt lgkmcnt(3)
	v_lshlrev_b32_e32 v136, 16, v126
	v_and_b32_e32 v137, 0xffff0000, v126
	v_fma_f32 v134, -v91, v93, v136
	v_fma_f32 v135, v91, v92, v137
	v_fma_f32 v92, v90, v92, v134
	v_fma_f32 v93, v90, v93, v135
	v_lshlrev_b32_e32 v136, 16, v127
	v_and_b32_e32 v137, 0xffff0000, v127
	v_fma_f32 v134, -v91, v93, v136
	v_fma_f32 v135, v91, v92, v137
	v_cvt_pk_bf16_f32 v130, v92, v93
	v_fma_f32 v92, v90, v92, v134
	v_fma_f32 v93, v90, v93, v135
	v_cvt_pk_bf16_f32 v131, v92, v93
	ds_write2_b32 v121, v130, v131 offset0:16 offset1:84
	s_waitcnt lgkmcnt(3)
	v_lshlrev_b32_e32 v136, 16, v128
	v_and_b32_e32 v137, 0xffff0000, v128
	v_fma_f32 v134, -v91, v93, v136
	v_fma_f32 v135, v91, v92, v137
	v_fma_f32 v92, v90, v92, v134
	v_fma_f32 v93, v90, v93, v135
	v_lshlrev_b32_e32 v136, 16, v129
	v_and_b32_e32 v137, 0xffff0000, v129
	v_fma_f32 v134, -v91, v93, v136
	v_fma_f32 v135, v91, v92, v137
	v_cvt_pk_bf16_f32 v132, v92, v93
	v_fma_f32 v92, v90, v92, v134
	v_fma_f32 v93, v90, v93, v135
	v_cvt_pk_bf16_f32 v133, v92, v93
	v_add_u32_e32 v83, 0x880, v83
	s_cmp_lt_u32 s2, 24
	ds_write2_b32 v121, v132, v133 offset0:152 offset1:220
	s_cbranch_scc1 .LBB0_439
	s_waitcnt lgkmcnt(0)
	ds_read_b128 v[122:125], v117 offset:32768
	ds_read_b128 v[126:129], v117 offset:32832
	v_or_b32_e32 v83, s14, v78
	v_mad_u32_u24 v83, v83, s15, v120
	s_mov_b32 s14, 32
	s_waitcnt lgkmcnt(1)
	v_mfma_f32_16x16x32_bf16 v[122:125], v[52:55], v[122:125], v[0:3]
	s_mov_b64 s[4:5], 0
	s_waitcnt lgkmcnt(0)
	v_mfma_f32_16x16x32_bf16 v[122:125], v[48:51], v[126:129], v[122:125]
	ds_read_b128 v[126:129], v117 offset:32896
	s_waitcnt lgkmcnt(0)
	v_mfma_f32_16x16x32_bf16 v[122:125], v[44:47], v[126:129], v[122:125]
	ds_read_b128 v[126:129], v117 offset:32960
	s_waitcnt lgkmcnt(0)
	v_mfma_f32_16x16x32_bf16 v[122:125], v[40:43], v[126:129], v[122:125]
	v_lshlrev_b32_e32 v126, 16, v102
	v_and_b32_e32 v127, 0xffff0000, v102
	s_nop 5
	v_pk_fma_f32 v[122:123], v[4:5], v[126:127], v[122:123]
	s_nop 0
	v_mul_f32_e32 v102, 0x3d372713, v122
	v_mul_f32_e32 v102, v122, v102
	v_fma_f32 v102, v122, v102, v122
	v_mul_f32_e32 v102, 0x3f4c422a, v102
	v_mul_f32_e32 v102, 0xc038aa3b, v102
	v_exp_f32_e32 v126, v102
	v_mul_f32_e32 v102, 0x3d372713, v123
	v_mul_f32_e32 v102, v123, v102
	v_fma_f32 v102, v123, v102, v123
	v_mul_f32_e32 v102, 0x3f4c422a, v102
	v_mul_f32_e32 v102, 0xc038aa3b, v102
	v_exp_f32_e32 v127, v102
	s_nop 0
	v_pk_add_f32 v[126:127], v[126:127], 1.0 op_sel_hi:[1,0]
	s_nop 0
	v_rcp_f32_e32 v127, v127
	v_rcp_f32_e32 v126, v126
	v_lshlrev_b32_e32 v102, 16, v103
	v_and_b32_e32 v103, 0xffff0000, v103
	v_pk_fma_f32 v[102:103], v[6:7], v[102:103], v[124:125]
	v_pk_mul_f32 v[122:123], v[122:123], v[126:127]
	v_mul_f32_e32 v121, 0x3d372713, v102
	v_mul_f32_e32 v121, v102, v121
	v_fma_f32 v121, v102, v121, v102
	v_mul_f32_e32 v121, 0x3f4c422a, v121
	v_mul_f32_e32 v121, 0xc038aa3b, v121
	v_exp_f32_e32 v124, v121
	v_mul_f32_e32 v121, 0x3d372713, v103
	v_mul_f32_e32 v121, v103, v121
	v_fma_f32 v121, v103, v121, v103
	v_mul_f32_e32 v121, 0x3f4c422a, v121
	v_mul_f32_e32 v121, 0xc038aa3b, v121
	v_exp_f32_e32 v125, v121
	v_cvt_pk_bf16_f32 v122, v122, v123
	v_pk_add_f32 v[124:125], v[124:125], 1.0 op_sel_hi:[1,0]
	s_nop 0
	v_rcp_f32_e32 v125, v125
	v_rcp_f32_e32 v124, v124
	s_nop 0
	v_pk_mul_f32 v[102:103], v[102:103], v[124:125]
	s_nop 0
	v_cvt_pk_bf16_f32 v123, v102, v103
	ds_write_b64 v83, v[122:123]
	ds_read_b128 v[122:125], v117 offset:37120
	ds_read_b128 v[126:129], v117 offset:37184
	s_waitcnt lgkmcnt(1)
	v_mfma_f32_16x16x32_bf16 v[122:125], v[52:55], v[122:125], v[0:3]
	v_lshlrev_b32_e32 v102, 16, v100
	v_and_b32_e32 v103, 0xffff0000, v100
	s_waitcnt lgkmcnt(0)
	v_mfma_f32_16x16x32_bf16 v[122:125], v[48:51], v[126:129], v[122:125]
	ds_read_b128 v[126:129], v117 offset:37248
	s_waitcnt lgkmcnt(0)
	v_mfma_f32_16x16x32_bf16 v[122:125], v[44:47], v[126:129], v[122:125]
	ds_read_b128 v[126:129], v117 offset:37312
	s_waitcnt lgkmcnt(0)
	v_mfma_f32_16x16x32_bf16 v[122:125], v[40:43], v[126:129], v[122:125]
	s_nop 7
	v_pk_fma_f32 v[102:103], v[4:5], v[102:103], v[122:123]
	s_nop 0
	v_mul_f32_e32 v100, 0x3d372713, v102
	v_mul_f32_e32 v100, v102, v100
	v_fma_f32 v100, v102, v100, v102
	v_mul_f32_e32 v100, 0x3f4c422a, v100
	v_mul_f32_e32 v100, 0xc038aa3b, v100
	v_exp_f32_e32 v122, v100
	v_mul_f32_e32 v100, 0x3d372713, v103
	v_mul_f32_e32 v100, v103, v100
	v_fma_f32 v100, v103, v100, v103
	v_mul_f32_e32 v100, 0x3f4c422a, v100
	v_mul_f32_e32 v100, 0xc038aa3b, v100
	v_exp_f32_e32 v123, v100
	s_nop 0
	v_pk_add_f32 v[122:123], v[122:123], 1.0 op_sel_hi:[1,0]
	s_nop 0
	v_rcp_f32_e32 v123, v123
	v_rcp_f32_e32 v122, v122
	v_lshlrev_b32_e32 v100, 16, v101
	v_and_b32_e32 v101, 0xffff0000, v101
	v_pk_fma_f32 v[100:101], v[6:7], v[100:101], v[124:125]
	v_pk_mul_f32 v[102:103], v[102:103], v[122:123]
	v_mul_f32_e32 v121, 0x3d372713, v100
	v_mul_f32_e32 v121, v100, v121
	v_fma_f32 v121, v100, v121, v100
	v_mul_f32_e32 v121, 0x3f4c422a, v121
	v_mul_f32_e32 v121, 0xc038aa3b, v121
	v_exp_f32_e32 v122, v121
	v_mul_f32_e32 v121, 0x3d372713, v101
	v_mul_f32_e32 v121, v101, v121
	v_fma_f32 v121, v101, v121, v101
	v_mul_f32_e32 v121, 0x3f4c422a, v121
	v_mul_f32_e32 v121, 0xc038aa3b, v121
	v_exp_f32_e32 v123, v121
	v_cvt_pk_bf16_f32 v102, v102, v103
	v_pk_add_f32 v[122:123], v[122:123], 1.0 op_sel_hi:[1,0]
	s_nop 0
	v_rcp_f32_e32 v123, v123
	v_rcp_f32_e32 v122, v122
	s_nop 0
	v_pk_mul_f32 v[100:101], v[100:101], v[122:123]
	s_and_b64 vcc, exec, s[12:13]
	v_cvt_pk_bf16_f32 v103, v100, v101
	ds_write_b64 v83, v[102:103] offset:8448
	s_nop 7
	s_cbranch_vccz .LBB0_438
	s_and_b64 vcc, exec, s[24:25]
	s_cbranch_vccz .LBB0_432
	s_ashr_i32 s29, s28, 31
	s_lshl_b64 s[2:3], s[28:29], 8
	v_lshl_add_u64 v[4:5], v[88:89], 0, s[2:3]
	v_add_co_u32_e32 v6, vcc, 0x645c000, v4
	s_nop 1
	v_addc_co_u32_e32 v7, vcc, 0, v5, vcc
	v_add_co_u32_e32 v4, vcc, 0x667c000, v4
	global_store_dword v[6:7], v92, off
	s_nop 0
	v_addc_co_u32_e32 v5, vcc, 0, v5, vcc
	global_store_dword v[4:5], v93, off
	s_branch .LBB0_432
